# SWA prompt output stores paired into 16-byte stores (permlane16_swap); stacked on the epilogue rewrites
# speedup vs baseline: 1.4042x; 1.0056x over previous
.LBB0_979:
	s_or_b64 exec, exec, s[52:53]
	ds_read_b128 v[194:197], v189
	ds_read_b128 v[198:201], v189 offset:64
	ds_read_b128 v[202:205], v189 offset:4352
	ds_read_b128 v[206:209], v189 offset:4416
	v_add_u32_e32 v61, s64, v170
	v_or_b32_e32 v193, v61, v142
	s_waitcnt vmcnt(1) lgkmcnt(3)
	v_mfma_f32_16x16x32_bf16 v[194:197], v[194:197], v[88:91], 0
	ds_read_b128 v[210:213], v189 offset:192
	v_sub_u32_e32 v62, v148, v193
	v_cvt_f32_i32_e32 v147, v62
	s_waitcnt lgkmcnt(2)
	v_mfma_f32_16x16x32_bf16 v[88:91], v[202:205], v[88:91], 0
	ds_read_b128 v[202:205], v189 offset:128
	v_cmp_gt_u32_e32 vcc, s57, v62
	v_cmp_lt_i32_e64 s[16:17], -1, v61
	v_mfma_f32_16x16x32_bf16 v[194:197], v[198:201], v[84:87], v[194:197]
	ds_read_b128 v[198:201], v189 offset:4480
	ds_read_b128 v[214:217], v189 offset:4544
	s_and_b64 vcc, s[16:17], vcc
	v_add_u32_e32 v61, v61, v162
	s_waitcnt lgkmcnt(2)
	v_mfma_f32_16x16x32_bf16 v[194:197], v[202:205], v[80:83], v[194:197]
	v_xad_u32 v202, v193, -1, v148
	v_cmp_gt_u32_e64 s[12:13], s57, v202
	s_and_b64 s[12:13], s[16:17], s[12:13]
	v_mfma_f32_16x16x32_bf16 v[84:87], v[206:209], v[84:87], v[88:91]
	s_waitcnt vmcnt(0)
	v_mfma_f32_16x16x32_bf16 v[88:91], v[210:213], v[76:79], v[194:197]
	s_waitcnt lgkmcnt(1)
	v_mfma_f32_16x16x32_bf16 v[80:83], v[198:201], v[80:83], v[84:87]
	s_waitcnt lgkmcnt(0)
	v_mfma_f32_16x16x32_bf16 v[76:79], v[214:217], v[76:79], v[80:83]
	s_nop 3
	v_mov_b32_e32 v150, v88
	v_pk_mul_f32 v[62:63], v[150:151], v[146:147]
	v_cvt_f32_i32_e32 v147, v202
	v_sub_f32_e32 v210, v62, v63
	v_max_f32_e32 v62, 0xf149f2ca, v210
	v_mov_b32_e32 v150, v89
	v_cndmask_b32_e32 v84, v191, v62, vcc
	v_pk_mul_f32 v[62:63], v[150:151], v[146:147]
	v_mov_b32_e32 v150, v90
	v_sub_f32_e32 v211, v62, v63
	v_or_b32_e32 v63, 2, v193
	v_sub_u32_e32 v63, v148, v63
	v_cvt_f32_i32_e32 v147, v63
	v_max_f32_e32 v62, v84, v211
	v_cndmask_b32_e64 v80, v84, v62, s[12:13]
	v_cmp_gt_u32_e64 s[14:15], s57, v63
	v_pk_mul_f32 v[62:63], v[150:151], v[146:147]
	s_and_b64 s[14:15], s[16:17], s[14:15]
	v_sub_f32_e32 v212, v62, v63
	v_or_b32_e32 v63, 3, v193
	v_sub_u32_e32 v63, v148, v63
	v_cvt_f32_i32_e32 v147, v63
	v_max_f32_e32 v62, v80, v212
	v_mov_b32_e32 v150, v91
	v_sub_u32_e32 v81, v148, v61
	v_cndmask_b32_e64 v80, v80, v62, s[14:15]
	v_cmp_gt_u32_e64 s[18:19], s57, v63
	v_pk_mul_f32 v[62:63], v[150:151], v[146:147]
	v_cvt_f32_i32_e32 v147, v81
	v_sub_f32_e32 v193, v62, v63
	v_max_f32_e32 v62, v80, v193
	s_and_b64 s[16:17], s[16:17], s[18:19]
	v_mov_b32_e32 v150, v76
	v_xad_u32 v76, v61, -1, v148
	v_cndmask_b32_e64 v80, v80, v62, s[16:17]
	v_pk_mul_f32 v[62:63], v[150:151], v[146:147]
	v_cvt_f32_i32_e32 v147, v76
	v_sub_f32_e32 v213, v62, v63
	v_max_f32_e32 v62, v80, v213
	v_cmp_gt_u32_e64 s[18:19], s57, v81
	v_mov_b32_e32 v150, v77
	v_cmp_gt_u32_e64 s[20:21], s57, v76
	v_cndmask_b32_e64 v80, v80, v62, s[18:19]
	v_pk_mul_f32 v[62:63], v[150:151], v[146:147]
	v_mov_b32_e32 v150, v78
	v_sub_f32_e32 v214, v62, v63
	v_or_b32_e32 v63, 2, v61
	v_sub_u32_e32 v77, v148, v63
	v_cvt_f32_i32_e32 v147, v77
	v_max_f32_e32 v62, v80, v80
	v_or_b32_e32 v61, 3, v61
	v_max_f32_e32 v62, v62, v214
	v_sub_u32_e32 v61, v148, v61
	v_cndmask_b32_e64 v76, v80, v62, s[20:21]
	v_pk_mul_f32 v[62:63], v[150:151], v[146:147]
	v_cvt_f32_i32_e32 v147, v61
	v_sub_f32_e32 v215, v62, v63
	v_max_f32_e32 v62, v76, v76
	v_max_f32_e32 v62, v62, v215
	v_cmp_gt_u32_e64 s[22:23], s57, v77
	v_mov_b32_e32 v150, v79
	v_cmp_gt_u32_e64 s[24:25], s57, v61
	v_cndmask_b32_e64 v76, v76, v62, s[22:23]
	v_pk_mul_f32 v[62:63], v[150:151], v[146:147]
	s_nop 0
	v_sub_f32_e32 v63, v62, v63
	v_max_f32_e32 v62, v76, v76
	v_max_f32_e32 v62, v62, v63
	v_cndmask_b32_e64 v61, v76, v62, s[24:25]
	v_and_b32_e32 v76, 64, v185
	v_xor_b32_e32 v62, 16, v185
	v_add_u32_e32 v76, 64, v76
	v_cmp_lt_i32_e64 s[26:27], v62, v76
	s_nop 1
	v_cndmask_b32_e64 v62, v185, v62, s[26:27]
	v_lshlrev_b32_e32 v147, 2, v62
	ds_bpermute_b32 v62, v147, v61
	v_max_f32_e32 v61, v61, v61
	s_waitcnt lgkmcnt(0)
	v_max_f32_e32 v62, v62, v62
	v_max_f32_e32 v61, v61, v62
	v_xor_b32_e32 v62, 32, v185
	v_cmp_lt_i32_e64 s[26:27], v62, v76
	ds_read_b64_tr_b16 v[206:207], v171 offset:0
	ds_read_b64_tr_b16 v[202:203], v171 offset:32
	ds_read_b64_tr_b16 v[198:199], v171 offset:64
	ds_read_b64_tr_b16 v[194:195], v171 offset:96
	ds_read_b64_tr_b16 v[88:89], v171 offset:128
	ds_read_b64_tr_b16 v[84:85], v171 offset:160
	ds_read_b64_tr_b16 v[80:81], v171 offset:192
	ds_read_b64_tr_b16 v[76:77], v171 offset:224
	ds_read_b64_tr_b16 v[208:209], v171 offset:4608
	ds_read_b64_tr_b16 v[204:205], v171 offset:4640
	ds_read_b64_tr_b16 v[200:201], v171 offset:4672
	ds_read_b64_tr_b16 v[196:197], v171 offset:4704
	ds_read_b64_tr_b16 v[90:91], v171 offset:4736
	ds_read_b64_tr_b16 v[86:87], v171 offset:4768
	ds_read_b64_tr_b16 v[82:83], v171 offset:4800
	ds_read_b64_tr_b16 v[78:79], v171 offset:4832
	s_waitcnt lgkmcnt(0)
	s_nop 1
	v_cndmask_b32_e64 v62, v185, v62, s[26:27]
	v_lshlrev_b32_e32 v150, 2, v62
	ds_bpermute_b32 v62, v150, v61
	s_waitcnt lgkmcnt(0)
	v_max3_f32 v61, v149, v61, v62
	v_sub_f32_e32 v62, v149, v61
	v_sub_f32_e32 v149, v210, v61
	v_sub_f32_e32 v210, v212, v61
	v_exp_f32_e32 v210, v210
	v_sub_f32_e32 v151, v211, v61
	v_sub_f32_e32 v193, v193, v61
	v_sub_f32_e32 v211, v214, v61
	v_cndmask_b32_e64 v216, 0, v210, s[14:15]
	v_sub_f32_e32 v210, v213, v61
	v_sub_f32_e32 v212, v215, v61
	v_sub_f32_e32 v63, v63, v61
	v_exp_f32_e32 v149, v149
	v_exp_f32_e32 v151, v151
	v_exp_f32_e32 v193, v193
	v_exp_f32_e32 v210, v210
	v_exp_f32_e32 v211, v211
	v_exp_f32_e32 v212, v212
	v_exp_f32_e32 v63, v63
	v_exp_f32_e32 v62, v62
	v_cndmask_b32_e32 v149, 0, v149, vcc
	v_cndmask_b32_e64 v151, 0, v151, s[12:13]
	v_cndmask_b32_e64 v193, 0, v193, s[16:17]
	v_cndmask_b32_e64 v214, 0, v210, s[18:19]
	v_cndmask_b32_e64 v215, 0, v211, s[20:21]
	v_cndmask_b32_e64 v217, 0, v212, s[22:23]
	v_cndmask_b32_e64 v63, 0, v63, s[24:25]
	v_cvt_pk_bf16_f32 v210, v149, v151
	v_cvt_pk_bf16_f32 v211, v216, v193
	v_cvt_pk_bf16_f32 v212, v214, v215
	v_cvt_pk_bf16_f32 v213, v217, v63
	v_pk_mul_f32 v[114:115], v[114:115], v[62:63] op_sel_hi:[1,0]
	v_pk_mul_f32 v[112:113], v[112:113], v[62:63] op_sel_hi:[1,0]
	v_pk_mul_f32 v[138:139], v[138:139], v[62:63] op_sel_hi:[1,0]
	v_pk_mul_f32 v[136:137], v[136:137], v[62:63] op_sel_hi:[1,0]
	v_mfma_f32_16x16x32_bf16 v[80:83], v[80:83], v[210:213], v[112:115]
	v_mul_f32_e64 v134, v134, v62
	v_mul_f32_e64 v135, v135, v62
	v_pk_mul_f32 v[132:133], v[132:133], v[62:63] op_sel_hi:[1,0]
	v_pk_mul_f32 v[130:131], v[130:131], v[62:63] op_sel_hi:[1,0]
	v_add_f32_e32 v112, 0, v149
	v_add_f32_e32 v112, v151, v112
	v_add_f32_e32 v112, v216, v112
	v_add_f32_e32 v112, v193, v112
	v_add_f32_e32 v112, v214, v112
	v_add_f32_e32 v112, v215, v112
	v_add_f32_e32 v112, v217, v112
	v_pk_mul_f32 v[128:129], v[128:129], v[62:63] op_sel_hi:[1,0]
	v_pk_mul_f32 v[126:127], v[126:127], v[62:63] op_sel_hi:[1,0]
	v_pk_mul_f32 v[124:125], v[124:125], v[62:63] op_sel_hi:[1,0]
	v_pk_mul_f32 v[122:123], v[122:123], v[62:63] op_sel_hi:[1,0]
	v_pk_mul_f32 v[120:121], v[120:121], v[62:63] op_sel_hi:[1,0]
	v_pk_mul_f32 v[118:119], v[118:119], v[62:63] op_sel_hi:[1,0]
	v_pk_mul_f32 v[116:117], v[116:117], v[62:63] op_sel_hi:[1,0]
	v_add_f32_e32 v63, v63, v112
	v_fmac_f32_e32 v63, v145, v62
	ds_bpermute_b32 v112, v147, v63
	v_pk_mul_f32 v[110:111], v[110:111], v[62:63] op_sel_hi:[1,0]
	v_pk_mul_f32 v[108:109], v[108:109], v[62:63] op_sel_hi:[1,0]
	s_ashr_i32 s12, s63, 3
	v_mov_b32_e32 v149, v60
	s_waitcnt lgkmcnt(0)
	v_add_f32_e32 v62, v63, v112
	ds_bpermute_b32 v63, v150, v62
	v_mfma_f32_16x16x32_bf16 v[108:111], v[76:79], v[210:213], v[108:111]
	s_sub_i32 s16, 5, s51
	s_ashr_i32 s13, s12, 31
	s_lshr_b32 s16, s30, s16
	s_waitcnt lgkmcnt(0)
	v_add_f32_e32 v76, v62, v63
	v_div_scale_f32 v77, s[14:15], v76, v76, 1.0
	v_rcp_f32_e32 v78, v77
	v_lshlrev_b64 v[62:63], s51, v[148:149]
	s_ashr_i32 s51, s50, 31
	s_lshl_b64 s[12:13], s[12:13], 12
	v_fma_f32 v79, -v77, v78, 1.0
	v_fmac_f32_e32 v78, v79, v78
	v_div_scale_f32 v79, vcc, 1.0, v76, 1.0
	v_mul_f32_e32 v112, v79, v78
	s_lshl_b64 s[14:15], s[50:51], 14
	v_fma_f32 v113, -v77, v112, v79
	s_add_u32 s12, s14, s12
	v_fmac_f32_e32 v112, v113, v78
	s_addc_u32 s13, s15, s13
	s_or_b32 s12, s12, s16
	v_mfma_f32_16x16x32_bf16 v[136:139], v[206:209], v[210:213], v[136:139]
	v_fma_f32 v77, -v77, v112, v79
	v_lshl_add_u64 v[62:63], s[12:13], 0, v[62:63]
	v_div_fmas_f32 v77, v77, v78, v112
	v_lshlrev_b64 v[112:113], 11, v[62:63]
	v_mfma_f32_16x16x32_bf16 v[132:135], v[202:205], v[210:213], v[132:135]
	v_lshl_add_u64 v[112:113], s[44:45], 0, v[112:113]
	s_lshl_b32 s30, s62, 8
	v_div_fixup_f32 v78, v77, v76, 1.0
	v_lshl_add_u64 v[112:113], v[112:113], 0, s[30:31]
	v_lshlrev_b32_e32 v114, 1, v142
	v_mov_b32_e32 v115, v60
	v_mfma_f32_16x16x32_bf16 v[128:131], v[198:201], v[210:213], v[128:131]
	v_lshl_add_u64 v[112:113], v[112:113], 0, v[114:115]
	v_bfe_u32 v248, v156, 4, 1
	v_mul_u32_u24_e32 v248, 24, v248
	v_mov_b32_e32 v249, 0
	v_lshl_add_u64 v[112:113], v[112:113], 0, v[248:249]
	v_pk_mul_f32 v[114:115], v[136:137], v[78:79] op_sel_hi:[1,0]
	v_pk_mul_f32 v[80:81], v[80:81], v[78:79] op_sel_hi:[1,0]
	v_mfma_f32_16x16x32_bf16 v[84:87], v[84:87], v[210:213], v[116:119]
	v_cvt_pk_bf16_f32 v114, v114, v115
	v_pk_mul_f32 v[82:83], v[82:83], v[78:79] op_sel_hi:[1,0]
	v_cvt_pk_bf16_f32 v80, v80, v81
	v_pk_mul_f32 v[116:117], v[138:139], v[78:79] op_sel_hi:[1,0]
	v_mfma_f32_16x16x32_bf16 v[124:127], v[194:197], v[210:213], v[124:127]
	v_cvt_pk_bf16_f32 v115, v116, v117
	v_mov_b32_e32 v248, v114
	v_mov_b32_e32 v249, v115
	v_pk_mul_f32 v[114:115], v[132:133], v[78:79] op_sel_hi:[1,0]
	v_mfma_f32_16x16x32_bf16 v[88:91], v[88:91], v[210:213], v[120:123]
	v_mul_f32_e64 v116, v134, v78
	v_mul_f32_e64 v117, v135, v78
	v_cvt_pk_bf16_f32 v114, v114, v115
	v_cvt_pk_bf16_f32 v115, v116, v117
	v_mov_b32_e32 v250, v114
	v_mov_b32_e32 v251, v115
	s_nop 1
	v_permlane16_swap_b32_e32 v248, v250
	v_permlane16_swap_b32_e32 v249, v251
	global_store_dwordx4 v[112:113], v[248:251], off
	v_pk_mul_f32 v[114:115], v[128:129], v[78:79] op_sel_hi:[1,0]
	v_pk_mul_f32 v[116:117], v[130:131], v[78:79] op_sel_hi:[1,0]
	v_cvt_pk_bf16_f32 v114, v114, v115
	v_cvt_pk_bf16_f32 v115, v116, v117
	v_cvt_pk_bf16_f32 v81, v82, v83
	v_mov_b32_e32 v248, v114
	v_mov_b32_e32 v249, v115
	v_pk_mul_f32 v[114:115], v[124:125], v[78:79] op_sel_hi:[1,0]
	v_pk_mul_f32 v[116:117], v[126:127], v[78:79] op_sel_hi:[1,0]
	v_pk_mul_f32 v[88:89], v[88:89], v[78:79] op_sel_hi:[1,0]
	v_pk_mul_f32 v[90:91], v[90:91], v[78:79] op_sel_hi:[1,0]
	v_pk_mul_f32 v[84:85], v[84:85], v[78:79] op_sel_hi:[1,0]
	v_pk_mul_f32 v[86:87], v[86:87], v[78:79] op_sel_hi:[1,0]
	v_mov_b32_e32 v252, v80
	v_mov_b32_e32 v253, v81
	v_pk_mul_f32 v[80:81], v[108:109], v[78:79] op_sel_hi:[1,0]
	v_pk_mul_f32 v[78:79], v[110:111], v[78:79] op_sel_hi:[1,0]
	v_cvt_pk_bf16_f32 v114, v114, v115
	v_cvt_pk_bf16_f32 v115, v116, v117
	v_cvt_pk_bf16_f32 v88, v88, v89
	v_cvt_pk_bf16_f32 v89, v90, v91
	v_cvt_pk_bf16_f32 v84, v84, v85
	v_cvt_pk_bf16_f32 v85, v86, v87
	v_cvt_pk_bf16_f32 v80, v80, v81
	v_cvt_pk_bf16_f32 v81, v78, v79
	v_mov_b32_e32 v250, v114
	v_mov_b32_e32 v251, v115
	s_nop 1
	v_permlane16_swap_b32_e32 v248, v250
	v_permlane16_swap_b32_e32 v249, v251
	global_store_dwordx4 v[112:113], v[248:251], off offset:64
	s_nop 1
	v_mov_b32_e32 v248, v88
	v_mov_b32_e32 v249, v89
	v_mov_b32_e32 v250, v84
	v_mov_b32_e32 v251, v85
	s_nop 1
	v_permlane16_swap_b32_e32 v248, v250
	v_permlane16_swap_b32_e32 v249, v251
	global_store_dwordx4 v[112:113], v[248:251], off offset:128
	v_mov_b32_e32 v254, v80
	v_mov_b32_e32 v255, v81
	s_nop 1
	v_permlane16_swap_b32_e32 v252, v254
	v_permlane16_swap_b32_e32 v253, v255
	global_store_dwordx4 v[112:113], v[252:255], off offset:192
	s_and_saveexec_b64 s[12:13], s[8:9]
	s_cbranch_execz .LBB0_946
	v_cmp_gt_f32_e32 vcc, s60, v76
	v_lshlrev_b64 v[62:63], 5, v[62:63]
	v_lshl_add_u64 v[62:63], s[46:47], 0, v[62:63]
	v_cndmask_b32_e64 v78, 0, 32, vcc
	v_ldexp_f32 v76, v76, v78
	v_log_f32_e32 v76, v76
	v_cndmask_b32_e32 v77, 0, v192, vcc
	s_lshl_b32 s30, s62, 2
	v_lshl_add_u64 v[62:63], v[62:63], 0, s[30:31]
	v_sub_f32_e32 v76, v76, v77
	v_add_f32_e32 v61, v61, v76
	v_mul_f32_e32 v61, 0x3f317218, v61
	global_store_dword v[62:63], v61, off
	s_branch .LBB0_946

	.amdhsa_kernel _Z10fwd_kernel6Params
		.amdhsa_group_segment_fixed_size 0
		.amdhsa_private_segment_fixed_size 0
		.amdhsa_kernarg_size 424
		.amdhsa_user_sgpr_count 2
		.amdhsa_user_sgpr_dispatch_ptr 0
		.amdhsa_user_sgpr_queue_ptr 0
		.amdhsa_user_sgpr_kernarg_segment_ptr 1
		.amdhsa_user_sgpr_dispatch_id 0
		.amdhsa_user_sgpr_kernarg_preload_length 0
		.amdhsa_user_sgpr_kernarg_preload_offset 0
		.amdhsa_user_sgpr_private_segment_size 0
		.amdhsa_uses_dynamic_stack 0
		.amdhsa_enable_private_segment 0
		.amdhsa_system_sgpr_workgroup_id_x 1
		.amdhsa_system_sgpr_workgroup_id_y 0
		.amdhsa_system_sgpr_workgroup_id_z 0
		.amdhsa_system_sgpr_workgroup_info 0
		.amdhsa_system_vgpr_workitem_id 2
		.amdhsa_next_free_vgpr 256
		.amdhsa_next_free_sgpr 102
		.amdhsa_accum_offset 256
		.amdhsa_reserve_vcc 1
		.amdhsa_float_round_mode_32 0
		.amdhsa_float_round_mode_16_64 0
		.amdhsa_float_denorm_mode_32 3
		.amdhsa_float_denorm_mode_16_64 3
		.amdhsa_dx10_clamp 1
		.amdhsa_ieee_mode 1
		.amdhsa_fp16_overflow 0
		.amdhsa_tg_split 0
		.amdhsa_exception_fp_ieee_invalid_op 0
		.amdhsa_exception_fp_denorm_src 0
		.amdhsa_exception_fp_ieee_div_zero 0
		.amdhsa_exception_fp_ieee_overflow 0
		.amdhsa_exception_fp_ieee_underflow 0
		.amdhsa_exception_fp_ieee_inexact 0
		.amdhsa_exception_int_div_zero 0
	.end_amdhsa_kernel

amdhsa.kernels:
  - .agpr_count:     0
    .args:
      - .offset:         0
        .size:           168
        .value_kind:     by_value
      - .offset:         168
        .size:           4
        .value_kind:     hidden_block_count_x
      - .offset:         172
        .size:           4
        .value_kind:     hidden_block_count_y
      - .offset:         176
        .size:           4
        .value_kind:     hidden_block_count_z
      - .offset:         180
        .size:           2
        .value_kind:     hidden_group_size_x
      - .offset:         182
        .size:           2
        .value_kind:     hidden_group_size_y
      - .offset:         184
        .size:           2
        .value_kind:     hidden_group_size_z
      - .offset:         186
        .size:           2
        .value_kind:     hidden_remainder_x
      - .offset:         188
        .size:           2
        .value_kind:     hidden_remainder_y
      - .offset:         190
        .size:           2
        .value_kind:     hidden_remainder_z
      - .offset:         208
        .size:           8
        .value_kind:     hidden_global_offset_x
      - .offset:         216
        .size:           8
        .value_kind:     hidden_global_offset_y
      - .offset:         224
        .size:           8
        .value_kind:     hidden_global_offset_z
      - .offset:         232
        .size:           2
        .value_kind:     hidden_grid_dims
      - .offset:         256
        .size:           8
        .value_kind:     hidden_multigrid_sync_arg
      - .offset:         288
        .size:           4
        .value_kind:     hidden_dynamic_lds_size
    .group_segment_fixed_size: 0
    .kernarg_segment_align: 8
    .kernarg_segment_size: 424
    .language:       OpenCL C
    .language_version:
      - 2
      - 0
    .max_flat_workgroup_size: 512
    .name:           _Z10fwd_kernel6Params
    .private_segment_fixed_size: 0
    .sgpr_count:     108
    .sgpr_spill_count: 21
    .symbol:         _Z10fwd_kernel6Params.kd
    .uniform_work_group_size: 1
    .uses_dynamic_stack: false
    .vgpr_count:     256
    .vgpr_spill_count: 0
    .wavefront_size: 64
